# attention softmax packed (v_pk_add for s-mx and row-sum) + packed merge, on lean-barrier stack
# baseline (speedup 1.0000x reference)
; __device__ __forceinline__ void at_task32(const Args& A, const At32& T, const At32& Tn, bf16x8 (&qf)[4], bf16x8 (&kf)[5][4], LAS unsigned char* lds, LAS unsigned char* vst, int lane) {
;     ...
;     float mx = -1e30f;
; #pragma unroll
;     for (int tile = 0; tile < 5; ++tile)
; #pragma unroll
;         for (int e = 0; e < 16; ++e) mx = fmaxf(mx, s[tile][e]);
;     { auto rr = __builtin_amdgcn_permlane32_swap(__float_as_uint(mx), __float_as_uint(mx), false, false); mx = fmaxf(__uint_as_float(rr[0]), __uint_as_float(rr[1])); }
;     float lsum = 0.f;
; #pragma unroll
;     for (int tile = 0; tile < 5; ++tile)
; #pragma unroll
;         for (int e = 0; e < 16; ++e) { const float p = __builtin_amdgcn_exp2f(s[tile][e] - mx); s[tile][e] = p; lsum += p; }
;     { auto rr = __builtin_amdgcn_permlane32_swap(__float_as_uint(lsum), __float_as_uint(lsum), false, false); lsum = __uint_as_float(rr[0]) + __uint_as_float(rr[1]); }
.LBB0_408:
	s_mov_b32 s6, 0xf149f2ca
	v_max3_f32 v80, v78, s6, v79
	v_max3_f32 v80, v80, v76, v77
	v_max3_f32 v80, v80, v74, v75
	v_max3_f32 v80, v80, v72, v73
	v_max3_f32 v80, v80, v70, v71
	v_max3_f32 v80, v80, v68, v69
	v_max3_f32 v80, v80, v66, v67
	v_max3_f32 v80, v80, v64, v65
	v_max3_f32 v80, v80, v48, v49
	v_max3_f32 v80, v80, v50, v51
	v_max3_f32 v80, v80, v52, v53
	v_max3_f32 v80, v80, v54, v55
	v_max3_f32 v80, v80, v56, v57
	v_max3_f32 v80, v80, v58, v59
	v_max3_f32 v80, v80, v60, v61
	v_max3_f32 v80, v80, v62, v63
	v_max3_f32 v80, v80, v32, v33
	v_max3_f32 v80, v80, v34, v35
	v_max3_f32 v80, v80, v36, v37
	v_max3_f32 v80, v80, v38, v39
	v_max3_f32 v80, v80, v40, v41
	v_max3_f32 v80, v80, v42, v43
	v_max3_f32 v80, v80, v44, v45
	v_max3_f32 v80, v80, v46, v47
	v_max3_f32 v80, v80, v16, v17
	v_max3_f32 v80, v80, v18, v19
	v_max3_f32 v80, v80, v20, v21
	v_max3_f32 v80, v80, v22, v23
	v_max3_f32 v80, v80, v24, v25
	v_max3_f32 v80, v80, v26, v27
	v_max3_f32 v80, v80, v28, v29
	v_max3_f32 v80, v80, v30, v31
	v_max3_f32 v80, v80, v0, v1
	v_max3_f32 v80, v80, v2, v3
	v_max3_f32 v80, v80, v4, v5
	v_max3_f32 v80, v80, v6, v7
	v_max3_f32 v80, v80, v8, v9
	v_max3_f32 v80, v80, v10, v11
	v_max3_f32 v80, v80, v12, v13
	v_max3_f32 v80, v80, v14, v15
	v_mov_b32_e32 v81, v80
	s_nop 1
	v_permlane32_swap_b32_e32 v80, v81
	s_nop 0
	v_max_f32_e32 v80, v80, v81
	v_mov_b32_e32 v178, 0
	v_mov_b32_e32 v242, v80
	v_mov_b32_e32 v243, v80
	v_mov_b32_e32 v179, 0
	v_mov_b32_e32 v211, 0
	v_pk_add_f32 v[110:111], v[16:17], v[242:243] neg_lo:[0,1] neg_hi:[0,1]
	v_pk_add_f32 v[112:113], v[18:19], v[242:243] neg_lo:[0,1] neg_hi:[0,1]
	v_pk_add_f32 v[114:115], v[20:21], v[242:243] neg_lo:[0,1] neg_hi:[0,1]
	v_pk_add_f32 v[116:117], v[22:23], v[242:243] neg_lo:[0,1] neg_hi:[0,1]
	v_pk_add_f32 v[118:119], v[24:25], v[242:243] neg_lo:[0,1] neg_hi:[0,1]
	v_sub_f32_e32 v120, v26, v80
	v_pk_add_f32 v[122:123], v[0:1], v[242:243] neg_lo:[0,1] neg_hi:[0,1]
	v_pk_add_f32 v[124:125], v[2:3], v[242:243] neg_lo:[0,1] neg_hi:[0,1]
	v_sub_f32_e32 v121, v4, v80
	v_pk_add_f32 v[78:79], v[78:79], v[242:243] neg_lo:[0,1] neg_hi:[0,1]
	v_pk_add_f32 v[76:77], v[76:77], v[242:243] neg_lo:[0,1] neg_hi:[0,1]
	v_pk_add_f32 v[74:75], v[74:75], v[242:243] neg_lo:[0,1] neg_hi:[0,1]
	v_pk_add_f32 v[72:73], v[72:73], v[242:243] neg_lo:[0,1] neg_hi:[0,1]
	v_pk_add_f32 v[70:71], v[70:71], v[242:243] neg_lo:[0,1] neg_hi:[0,1]
	v_pk_add_f32 v[68:69], v[68:69], v[242:243] neg_lo:[0,1] neg_hi:[0,1]
	v_pk_add_f32 v[66:67], v[66:67], v[242:243] neg_lo:[0,1] neg_hi:[0,1]
	v_pk_add_f32 v[64:65], v[64:65], v[242:243] neg_lo:[0,1] neg_hi:[0,1]
	v_exp_f32_e32 v0, v78
	v_exp_f32_e32 v1, v79
	v_exp_f32_e32 v2, v76
	v_pk_add_f32 v[178:179], v[0:1], v[178:179]
	v_exp_f32_e32 v3, v77
	v_exp_f32_e32 v4, v74
	v_pk_add_f32 v[178:179], v[2:3], v[178:179]
	v_exp_f32_e32 v16, v75
	v_exp_f32_e32 v17, v72
	v_exp_f32_e32 v18, v73
	v_pk_add_f32 v[178:179], v[16:17], v[178:179]
	v_exp_f32_e32 v19, v70
	v_exp_f32_e32 v20, v71
	v_pk_add_f32 v[178:179], v[18:19], v[178:179]
	v_exp_f32_e32 v21, v68
	v_exp_f32_e32 v22, v69
	v_pk_add_f32 v[178:179], v[20:21], v[178:179]
	v_exp_f32_e32 v23, v66
	v_exp_f32_e32 v24, v67
	v_pk_add_f32 v[178:179], v[22:23], v[178:179]
	v_exp_f32_e32 v25, v64
	v_exp_f32_e32 v26, v65
	v_pk_add_f32 v[178:179], v[24:25], v[178:179]
	v_pk_add_f32 v[48:49], v[48:49], v[242:243] neg_lo:[0,1] neg_hi:[0,1]
	v_pk_add_f32 v[50:51], v[50:51], v[242:243] neg_lo:[0,1] neg_hi:[0,1]
	v_pk_add_f32 v[52:53], v[52:53], v[242:243] neg_lo:[0,1] neg_hi:[0,1]
	v_pk_add_f32 v[54:55], v[54:55], v[242:243] neg_lo:[0,1] neg_hi:[0,1]
	v_pk_add_f32 v[56:57], v[56:57], v[242:243] neg_lo:[0,1] neg_hi:[0,1]
	v_pk_add_f32 v[58:59], v[58:59], v[242:243] neg_lo:[0,1] neg_hi:[0,1]
	v_pk_add_f32 v[60:61], v[60:61], v[242:243] neg_lo:[0,1] neg_hi:[0,1]
	v_pk_add_f32 v[62:63], v[62:63], v[242:243] neg_lo:[0,1] neg_hi:[0,1]
	v_exp_f32_e32 v94, v48
	v_exp_f32_e32 v95, v49
	v_exp_f32_e32 v96, v50
	v_pk_add_f32 v[178:179], v[94:95], v[178:179]
	v_exp_f32_e32 v97, v51
	v_exp_f32_e32 v98, v52
	v_pk_add_f32 v[178:179], v[96:97], v[178:179]
	v_exp_f32_e32 v99, v53
	v_exp_f32_e32 v100, v54
	v_pk_add_f32 v[178:179], v[98:99], v[178:179]
	v_exp_f32_e32 v101, v55
	v_exp_f32_e32 v102, v56
	v_pk_add_f32 v[178:179], v[100:101], v[178:179]
	v_exp_f32_e32 v103, v57
	v_exp_f32_e32 v104, v58
	v_pk_add_f32 v[178:179], v[102:103], v[178:179]
	v_exp_f32_e32 v105, v59
	v_exp_f32_e32 v106, v60
	v_pk_add_f32 v[178:179], v[104:105], v[178:179]
	v_exp_f32_e32 v107, v61
	v_exp_f32_e32 v108, v62
	v_pk_add_f32 v[178:179], v[106:107], v[178:179]
	v_exp_f32_e32 v109, v63
	v_pk_add_f32 v[32:33], v[32:33], v[242:243] neg_lo:[0,1] neg_hi:[0,1]
	v_pk_add_f32 v[34:35], v[34:35], v[242:243] neg_lo:[0,1] neg_hi:[0,1]
	v_pk_add_f32 v[36:37], v[36:37], v[242:243] neg_lo:[0,1] neg_hi:[0,1]
	v_pk_add_f32 v[38:39], v[38:39], v[242:243] neg_lo:[0,1] neg_hi:[0,1]
	v_pk_add_f32 v[40:41], v[40:41], v[242:243] neg_lo:[0,1] neg_hi:[0,1]
	v_pk_add_f32 v[42:43], v[42:43], v[242:243] neg_lo:[0,1] neg_hi:[0,1]
	v_pk_add_f32 v[44:45], v[44:45], v[242:243] neg_lo:[0,1] neg_hi:[0,1]
	v_pk_add_f32 v[46:47], v[46:47], v[242:243] neg_lo:[0,1] neg_hi:[0,1]
	v_exp_f32_e32 v77, v32
	v_pk_add_f32 v[178:179], v[108:109], v[178:179]
	v_exp_f32_e32 v78, v33
	v_exp_f32_e32 v79, v34
	v_exp_f32_e32 v81, v35
	v_pk_add_f32 v[178:179], v[78:79], v[178:179]
	v_exp_f32_e32 v82, v36
	v_exp_f32_e32 v83, v37
	v_exp_f32_e32 v84, v38
	v_pk_add_f32 v[178:179], v[82:83], v[178:179]
	v_exp_f32_e32 v85, v39
	v_exp_f32_e32 v86, v40
	v_pk_add_f32 v[178:179], v[84:85], v[178:179]
	v_exp_f32_e32 v87, v41
	v_exp_f32_e32 v88, v42
; #define LAS __attribute__((address_space(3)))
; __device__ __forceinline__ void at_task32(const Args& A, const At32& T, const At32& Tn, bf16x8 (&qf)[4], bf16x8 (&kf)[5][4], LAS unsigned char* lds, LAS unsigned char* vst, int lane) {
;     ...
;     for (int tile = 0; tile < 5; ++tile)
; #pragma unroll
;         for (int e = 0; e < 16; ++e) { const float p = __builtin_amdgcn_exp2f(s[tile][e] - mx); s[tile][e] = p; lsum += p; }
;     { auto rr = __builtin_amdgcn_permlane32_swap(__float_as_uint(lsum), __float_as_uint(lsum), false, false); lsum = __uint_as_float(rr[0]) + __uint_as_float(rr[1]); }
;     __builtin_amdgcn_sched_barrier(0);
;     u32x4 vr[8];
; #pragma unroll
;     for (int idx = 0; idx < 8; ++idx) { const int row = 8 * idx + (lane >> 3); int lk = lk0 + row; lk = lk < 0 ? 0 : (lk > L - 1 ? L - 1 : lk);
;         vr[idx] = *(const u32x4*)(Vb + ((unsigned)((lk << dsh) + r) * 2048u + 16u * (lane & 7))); }
;     f32x16 o[2];
; #pragma unroll
;     for (int db = 0; db < 2; ++db)
; #pragma unroll
;         for (int e = 0; e < 16; ++e) o[db][e] = 0.f;
;     const int i16 = lane & 15;
;     const LAS unsigned char* trb = vst + (4 * h + (i16 >> 2)) * VS_STRIDE + (((lane >> 4) & 1) * 16 + 4 * (i16 & 3)) * 2;
; #pragma unroll
;     for (int tile = 0; tile < 5; ++tile) {
; #pragma unroll
;         for (int it = 0; it < 4; ++it) { const int idx = it * 64 + lane, row = idx >> 3, ch = idx & 7; *(LAS u32x4*)(vst + row * VS_STRIDE + ch * 16) = vr[(tile & 1) * 4 + it]; }
;         if (tile < 3) {
; #pragma unroll
;             for (int it = 0; it < 4; ++it) { const int row = 32 * (tile + 2) + 8 * it + (lane >> 3); int lk = lk0 + row; lk = lk < 0 ? 0 : (lk > L - 1 ? L - 1 : lk);
;                 vr[(tile & 1) * 4 + it] = *(const u32x4*)(Vb + ((unsigned)((lk << dsh) + r) * 2048u + 16u * (lane & 7))); }
;         }
;         bf16x8 pf[2];
; #pragma unroll
;         for (int ks = 0; ks < 2; ++ks) { u32x4 pw; pw.x = cvt_pk_bf16(s[tile][8 * ks + 0], s[tile][8 * ks + 1]); pw.y = cvt_pk_bf16(s[tile][8 * ks + 2], s[tile][8 * ks + 3]);
;             pw.z = cvt_pk_bf16(s[tile][8 * ks + 4], s[tile][8 * ks + 5]); pw.w = cvt_pk_bf16(s[tile][8 * ks + 6], s[tile][8 * ks + 7]); pf[ks] = __builtin_bit_cast(bf16x8, pw); }
;         asm volatile("s_waitcnt lgkmcnt(0)" ::: "memory");
; #pragma unroll
;         for (int ks = 0; ks < 2; ++ks)
; #pragma unroll
	v_pk_add_f32 v[178:179], v[86:87], v[178:179]
	v_exp_f32_e32 v89, v43
	v_exp_f32_e32 v90, v44
	v_pk_add_f32 v[178:179], v[88:89], v[178:179]
	v_exp_f32_e32 v91, v45
	v_exp_f32_e32 v92, v46
	v_pk_add_f32 v[178:179], v[90:91], v[178:179]
	v_exp_f32_e32 v93, v47
	v_pk_add_f32 v[28:29], v[28:29], v[242:243] neg_lo:[0,1] neg_hi:[0,1]
	v_pk_add_f32 v[30:31], v[30:31], v[242:243] neg_lo:[0,1] neg_hi:[0,1]
	v_sub_f32_e32 v27, v27, v80
	v_exp_f32_e32 v61, v110
	v_pk_add_f32 v[178:179], v[92:93], v[178:179]
	v_exp_f32_e32 v62, v111
	v_exp_f32_e32 v63, v112
	v_exp_f32_e32 v64, v113
	v_pk_add_f32 v[178:179], v[62:63], v[178:179]
	v_exp_f32_e32 v65, v114
	v_exp_f32_e32 v66, v115
	v_pk_add_f32 v[178:179], v[64:65], v[178:179]
	v_exp_f32_e32 v67, v116
	v_exp_f32_e32 v68, v117
	v_pk_add_f32 v[178:179], v[66:67], v[178:179]
	v_exp_f32_e32 v69, v118
	v_exp_f32_e32 v70, v119
	v_pk_add_f32 v[178:179], v[68:69], v[178:179]
	v_exp_f32_e32 v71, v120
	v_exp_f32_e32 v72, v27
	v_pk_add_f32 v[178:179], v[70:71], v[178:179]
	v_exp_f32_e32 v73, v28
	v_exp_f32_e32 v74, v29
	v_pk_add_f32 v[178:179], v[72:73], v[178:179]
	v_exp_f32_e32 v75, v30
	v_exp_f32_e32 v76, v31
	v_pk_add_f32 v[178:179], v[74:75], v[178:179]
	v_pk_add_f32 v[6:7], v[6:7], v[242:243] neg_lo:[0,1] neg_hi:[0,1]
	v_pk_add_f32 v[8:9], v[8:9], v[242:243] neg_lo:[0,1] neg_hi:[0,1]
	v_pk_add_f32 v[10:11], v[10:11], v[242:243] neg_lo:[0,1] neg_hi:[0,1]
	v_pk_add_f32 v[12:13], v[12:13], v[242:243] neg_lo:[0,1] neg_hi:[0,1]
	v_pk_add_f32 v[14:15], v[14:15], v[242:243] neg_lo:[0,1] neg_hi:[0,1]
	v_sub_f32_e32 v5, v5, v80
	v_exp_f32_e32 v56, v122
	v_pk_add_f32 v[178:179], v[76:77], v[178:179]
	v_exp_f32_e32 v57, v123
	v_exp_f32_e32 v58, v124
	v_pk_add_f32 v[178:179], v[56:57], v[178:179]
	v_exp_f32_e32 v59, v125
	v_exp_f32_e32 v60, v121
	v_pk_add_f32 v[178:179], v[58:59], v[178:179]
	v_exp_f32_e32 v112, v5
	v_pk_add_f32 v[178:179], v[60:61], v[178:179]
	v_exp_f32_e32 v113, v6
	v_exp_f32_e32 v114, v7
	v_pk_add_f32 v[178:179], v[112:113], v[178:179]
	v_exp_f32_e32 v115, v8
	v_exp_f32_e32 v116, v9
	v_pk_add_f32 v[178:179], v[114:115], v[178:179]
	v_exp_f32_e32 v117, v10
	v_exp_f32_e32 v118, v11
	v_pk_add_f32 v[178:179], v[116:117], v[178:179]
	v_exp_f32_e32 v119, v12
	v_exp_f32_e32 v120, v13
	v_pk_add_f32 v[178:179], v[118:119], v[178:179]
	v_exp_f32_e32 v121, v14
	v_exp_f32_e32 v122, v15
	v_pk_add_f32 v[178:179], v[120:121], v[178:179]
	s_nop 1
	v_add_f32_e32 v211, v4, v211
	s_ashr_i32 s6, s22, 4
	v_add_f32_e32 v211, v26, v211
	s_ashr_i32 s7, s6, 31
	v_add_f32_e32 v211, v81, v211
	s_lshl_b32 s22, s22, 7
	v_add_f32_e32 v211, v122, v211
	s_lshl_b64 s[6:7], s[6:7], 24
	v_add_f32_e32 v178, v178, v179
	v_readlane_b32 vcc_lo, v253, 58
	v_add_f32_e32 v110, v211, v178
	s_add_u32 s6, vcc_lo, s6
	v_mov_b32_e32 v111, v110
	v_readlane_b32 vcc_lo, v253, 59
	s_addc_u32 s7, vcc_lo, s7
	s_and_b32 s22, s22, 0x780
	s_add_u32 s6, s6, s22
	s_nop 0
	v_permlane32_swap_b32_e32 v110, v111
	s_addc_u32 s7, s7, 0
	s_add_i32 s34, s34, -1
	s_movk_i32 s22, 0xffdf
	v_add_u32_e32 v123, s3, v172
	s_lshl_b32 s3, s28, 7
	s_and_b32 s3, s3, 0x780
	v_min_i32_e32 v5, s34, v123
	v_cmp_lt_i32_e32 vcc, -1, v123
	s_waitcnt vmcnt(4)
	ds_write_b128 v201, v[212:215]
	ds_write_b128 v201, v[216:219] offset:1280
	ds_write_b128 v201, v[220:223] offset:2560
	ds_write_b128 v201, v[224:227] offset:3840
	v_cndmask_b32_e32 v5, 0, v5, vcc
	v_lshlrev_b32_e32 v5, s27, v5
	v_add_u32_e32 v5, s31, v5
	v_lshl_or_b32 v5, v5, 11, v173
	global_load_dwordx4 v[48:51], v5, s[6:7]
	v_add_u32_e32 v5, 8, v123
	v_min_i32_e32 v5, s34, v5
	v_cmp_lt_i32_e32 vcc, -9, v123
	s_nop 1
	v_cndmask_b32_e32 v5, 0, v5, vcc
	v_lshlrev_b32_e32 v5, s27, v5
	v_add_u32_e32 v5, s31, v5
	v_lshl_or_b32 v5, v5, 11, v173
	global_load_dwordx4 v[52:55], v5, s[6:7]
	v_add_u32_e32 v5, 16, v123
	v_min_i32_e32 v5, s34, v5
	v_cmp_lt_i32_e32 vcc, s19, v123
	s_nop 1
	v_cndmask_b32_e32 v5, 0, v5, vcc
	v_lshlrev_b32_e32 v5, s27, v5
	v_add_u32_e32 v5, s31, v5
	v_lshl_or_b32 v5, v5, 11, v173
	global_load_dwordx4 v[124:127], v5, s[6:7]
	v_add_u32_e32 v5, 24, v123
	v_min_i32_e32 v5, s34, v5
	v_cmp_lt_i32_e32 vcc, s12, v123
	s_nop 1
	v_cndmask_b32_e32 v5, 0, v5, vcc
	v_lshlrev_b32_e32 v5, s27, v5
	v_add_u32_e32 v5, s31, v5
	v_lshl_or_b32 v5, v5, 11, v173
	global_load_dwordx4 v[128:131], v5, s[6:7]
	v_cvt_pk_bf16_f32 v0, v0, v1
	v_cvt_pk_bf16_f32 v1, v2, v3
	v_cvt_pk_bf16_f32 v2, v4, v16
	v_cvt_pk_bf16_f32 v3, v17, v18
	v_cvt_pk_bf16_f32 v132, v19, v20
	v_cvt_pk_bf16_f32 v133, v21, v22
	v_cvt_pk_bf16_f32 v134, v23, v24
	v_cvt_pk_bf16_f32 v135, v25, v26
	s_waitcnt lgkmcnt(0)
	ds_read_b64_tr_b16 v[4:5], v202
	ds_read_b64_tr_b16 v[6:7], v202 offset:1280
	s_waitcnt lgkmcnt(0)
	v_mfma_f32_32x32x16_bf16 v[16:31], v[4:7], v[0:3], 0
	ds_read_b64_tr_b16 v[4:5], v202 offset:64
	ds_read_b64_tr_b16 v[6:7], v202 offset:1344
	ds_read_b64_tr_b16 v[136:137], v202 offset:2560
	ds_read_b64_tr_b16 v[138:139], v202 offset:3840
	v_cmp_lt_i32_e32 vcc, s22, v123
	s_waitcnt lgkmcnt(0)
	v_mfma_f32_32x32x16_bf16 v[16:31], v[136:139], v[132:135], v[16:31]
	ds_read_b64_tr_b16 v[136:137], v202 offset:2624
	ds_read_b64_tr_b16 v[138:139], v202 offset:3904
	s_waitcnt lgkmcnt(0)
	s_waitcnt vmcnt(7)
	ds_write_b128 v201, v[228:231]
	s_waitcnt vmcnt(6)
	ds_write_b128 v201, v[232:235] offset:1280
	s_waitcnt vmcnt(5)
	ds_write_b128 v201, v[248:251] offset:2560
	s_waitcnt vmcnt(4)
; __device__ __forceinline__ void at_task32(const Args& A, const At32& T, const At32& Tn, bf16x8 (&qf)[4], bf16x8 (&kf)[5][4], LAS unsigned char* lds, LAS unsigned char* vst, int lane) {
;     ...
;     { auto rr = __builtin_amdgcn_permlane32_swap(__float_as_uint(lsum), __float_as_uint(lsum), false, false); lsum = __uint_as_float(rr[0]) + __uint_as_float(rr[1]); }
;     __builtin_amdgcn_sched_barrier(0);
;     u32x4 vr[8];
; #pragma unroll
;     for (int idx = 0; idx < 8; ++idx) { const int row = 8 * idx + (lane >> 3); int lk = lk0 + row; lk = lk < 0 ? 0 : (lk > L - 1 ? L - 1 : lk);
;         vr[idx] = *(const u32x4*)(Vb + ((unsigned)((lk << dsh) + r) * 2048u + 16u * (lane & 7))); }
;     f32x16 o[2];
; #pragma unroll
;     for (int db = 0; db < 2; ++db)
; #pragma unroll
;         for (int e = 0; e < 16; ++e) o[db][e] = 0.f;
;     const int i16 = lane & 15;
;     const LAS unsigned char* trb = vst + (4 * h + (i16 >> 2)) * VS_STRIDE + (((lane >> 4) & 1) * 16 + 4 * (i16 & 3)) * 2;
; #pragma unroll
;     for (int tile = 0; tile < 5; ++tile) {
; #pragma unroll
;         for (int it = 0; it < 4; ++it) { const int idx = it * 64 + lane, row = idx >> 3, ch = idx & 7; *(LAS u32x4*)(vst + row * VS_STRIDE + ch * 16) = vr[(tile & 1) * 4 + it]; }
;         if (tile < 3) {
; #pragma unroll
;             for (int it = 0; it < 4; ++it) { const int row = 32 * (tile + 2) + 8 * it + (lane >> 3); int lk = lk0 + row; lk = lk < 0 ? 0 : (lk > L - 1 ? L - 1 : lk);
;                 vr[(tile & 1) * 4 + it] = *(const u32x4*)(Vb + ((unsigned)((lk << dsh) + r) * 2048u + 16u * (lane & 7))); }
;         }
;         bf16x8 pf[2];
; #pragma unroll
;         for (int ks = 0; ks < 2; ++ks) { u32x4 pw; pw.x = cvt_pk_bf16(s[tile][8 * ks + 0], s[tile][8 * ks + 1]); pw.y = cvt_pk_bf16(s[tile][8 * ks + 2], s[tile][8 * ks + 3]);
;             pw.z = cvt_pk_bf16(s[tile][8 * ks + 4], s[tile][8 * ks + 5]); pw.w = cvt_pk_bf16(s[tile][8 * ks + 6], s[tile][8 * ks + 7]); pf[ks] = __builtin_bit_cast(bf16x8, pw); }
;         asm volatile("s_waitcnt lgkmcnt(0)" ::: "memory");
; #pragma unroll
;         for (int ks = 0; ks < 2; ++ks)
; #pragma unroll
;             for (int db = 0; db < 2; ++db) { const bf16x8 af = tr_pair(trb + (16 * ks) * VS_STRIDE + db * 64, trb + (16 * ks + 8) * VS_STRIDE + db * 64);
;                 o[db] = __builtin_amdgcn_mfma_f32_32x32x16_bf16(af, pf[ks], o[db], 0, 0, 0); }
	ds_write_b128 v201, v[236:239] offset:3840
	v_add_u32_e32 v32, 32, v123
	v_min_i32_e32 v32, s34, v32
	v_add_u32_e32 v36, 40, v123
	v_cndmask_b32_e32 v32, 0, v32, vcc
	v_min_i32_e32 v36, s34, v36
	v_cmp_lt_i32_e32 vcc, s29, v123
	v_add_u32_e32 v40, 48, v123
	v_min_i32_e32 v40, s34, v40
	v_cndmask_b32_e32 v36, 0, v36, vcc
	v_cmp_lt_i32_e32 vcc, s2, v123
	v_add_u32_e32 v44, 56, v123
	v_mfma_f32_32x32x16_bf16 v[0:15], v[4:7], v[0:3], 0
	v_cndmask_b32_e32 v40, 0, v40, vcc
	v_min_i32_e32 v44, s34, v44
	v_cmp_lt_i32_e32 vcc, s18, v123
	v_lshlrev_b32_e32 v32, s27, v32
	v_lshlrev_b32_e32 v36, s27, v36
	v_cndmask_b32_e32 v44, 0, v44, vcc
	v_lshlrev_b32_e32 v40, s27, v40
	v_lshlrev_b32_e32 v44, s27, v44
	v_add_u32_e32 v32, s31, v32
	v_add_u32_e32 v36, s31, v36
	v_add_u32_e32 v40, s31, v40
	v_add_u32_e32 v44, s31, v44
	v_lshl_or_b32 v32, v32, 11, v173
	v_lshl_or_b32 v36, v36, 11, v173
	v_lshl_or_b32 v40, v40, 11, v173
	v_lshl_or_b32 v44, v44, 11, v173
	global_load_dwordx4 v[32:35], v32, s[6:7]
	s_waitcnt lgkmcnt(4)
	v_mfma_f32_32x32x16_bf16 v[0:15], v[136:139], v[132:135], v[0:15]
	global_load_dwordx4 v[36:39], v36, s[6:7]
	s_movk_i32 s18, 0xffbf
	global_load_dwordx4 v[40:43], v40, s[6:7]
	v_cmp_lt_i32_e32 vcc, s18, v123
	global_load_dwordx4 v[44:47], v44, s[6:7]
	v_cvt_pk_bf16_f32 v94, v94, v95
	v_cvt_pk_bf16_f32 v95, v96, v97
	v_cvt_pk_bf16_f32 v96, v98, v99
	v_cvt_pk_bf16_f32 v97, v100, v101
	v_cvt_pk_bf16_f32 v98, v102, v103
	v_cvt_pk_bf16_f32 v99, v104, v105
	v_cvt_pk_bf16_f32 v100, v106, v107
	v_cvt_pk_bf16_f32 v101, v108, v109
	s_waitcnt lgkmcnt(0)
	ds_read_b64_tr_b16 v[102:103], v202
	ds_read_b64_tr_b16 v[104:105], v202 offset:1280
	s_waitcnt lgkmcnt(0)
	v_mfma_f32_32x32x16_bf16 v[16:31], v[102:105], v[94:97], v[16:31]
	ds_read_b64_tr_b16 v[102:103], v202 offset:64
	ds_read_b64_tr_b16 v[104:105], v202 offset:1344
	s_movk_i32 s2, 0xffdf
	s_waitcnt lgkmcnt(0)
	v_mfma_f32_32x32x16_bf16 v[0:15], v[102:105], v[94:97], v[0:15]
	ds_read_b64_tr_b16 v[94:95], v202 offset:2560
	ds_read_b64_tr_b16 v[96:97], v202 offset:3840
	s_waitcnt lgkmcnt(0)
	v_mfma_f32_32x32x16_bf16 v[16:31], v[94:97], v[98:101], v[16:31]
	ds_read_b64_tr_b16 v[94:95], v202 offset:2624
	ds_read_b64_tr_b16 v[96:97], v202 offset:3904
	s_waitcnt lgkmcnt(0)
	s_waitcnt vmcnt(7)
	ds_write_b128 v201, v[48:51]
	s_waitcnt vmcnt(6)
	ds_write_b128 v201, v[52:55] offset:1280
	s_waitcnt vmcnt(5)
	ds_write_b128 v201, v[124:127] offset:2560
	s_waitcnt vmcnt(4)
	ds_write_b128 v201, v[128:131] offset:3840
	v_add_u32_e32 v48, 64, v123
	v_min_i32_e32 v48, s34, v48
	v_add_u32_e32 v52, 0x48, v123
	v_cndmask_b32_e32 v48, 0, v48, vcc
	s_waitcnt lgkmcnt(4)
	v_mfma_f32_32x32x16_bf16 v[0:15], v[94:97], v[98:101], v[0:15]
	v_min_i32_e32 v52, s34, v52
	v_cmp_lt_i32_e32 vcc, s20, v123
	v_add_u32_e32 v94, 0x50, v123
	v_lshlrev_b32_e32 v48, s27, v48
	v_cndmask_b32_e32 v52, 0, v52, vcc
	v_min_i32_e32 v94, s34, v94
	v_cmp_lt_i32_e32 vcc, s13, v123
	v_add_u32_e32 v98, 0x58, v123
	v_add_u32_e32 v48, s31, v48
	v_lshlrev_b32_e32 v52, s27, v52
	v_cndmask_b32_e32 v94, 0, v94, vcc
	v_min_i32_e32 v98, s34, v98
	v_cmp_lt_i32_e32 vcc, s15, v123
	v_lshl_or_b32 v48, v48, 11, v173
	v_add_u32_e32 v52, s31, v52
	v_lshlrev_b32_e32 v94, s27, v94
	v_cndmask_b32_e32 v98, 0, v98, vcc
	global_load_dwordx4 v[48:51], v48, s[6:7]
	v_lshl_or_b32 v52, v52, 11, v173
	v_add_u32_e32 v94, s31, v94
	v_lshlrev_b32_e32 v98, s27, v98
	global_load_dwordx4 v[52:55], v52, s[6:7]
	v_lshl_or_b32 v94, v94, 11, v173
	v_add_u32_e32 v98, s31, v98
	global_load_dwordx4 v[94:97], v94, s[6:7]
	v_lshl_or_b32 v98, v98, 11, v173
	global_load_dwordx4 v[98:101], v98, s[6:7]
	v_cvt_pk_bf16_f32 v102, v77, v78
	v_cvt_pk_bf16_f32 v103, v79, v81
	v_cvt_pk_bf16_f32 v104, v82, v83
	v_cvt_pk_bf16_f32 v105, v84, v85
	v_cvt_pk_bf16_f32 v82, v86, v87
	v_cvt_pk_bf16_f32 v83, v88, v89
	v_cvt_pk_bf16_f32 v84, v90, v91
	v_cvt_pk_bf16_f32 v85, v92, v93
	s_waitcnt lgkmcnt(0)
	ds_read_b64_tr_b16 v[86:87], v202
	ds_read_b64_tr_b16 v[88:89], v202 offset:1280
	s_waitcnt lgkmcnt(0)
	v_mfma_f32_32x32x16_bf16 v[16:31], v[86:89], v[102:105], v[16:31]
	ds_read_b64_tr_b16 v[86:87], v202 offset:64
	ds_read_b64_tr_b16 v[88:89], v202 offset:1344
	s_ashr_i32 s6, s28, 4
	s_ashr_i32 s7, s6, 31
	s_lshl_b64 s[6:7], s[6:7], 24
	s_or_b32 s3, s6, s3
	v_readlane_b32 s12, v253, 49
	v_readlane_b32 s13, v253, 50
	s_waitcnt lgkmcnt(0)
	v_mfma_f32_32x32x16_bf16 v[0:15], v[86:89], v[102:105], v[0:15]
	ds_read_b64_tr_b16 v[86:87], v202 offset:2560
	ds_read_b64_tr_b16 v[88:89], v202 offset:3840
	s_add_u32 s34, s12, s3
	s_addc_u32 s35, s13, s7
	s_lshr_b32 s22, 0x2000, s23
	v_add_f32_e32 v81, v110, v111
	s_movk_i32 s13, 0xffdf
	s_waitcnt lgkmcnt(0)
	v_mfma_f32_32x32x16_bf16 v[16:31], v[86:89], v[82:85], v[16:31]
	ds_read_b64_tr_b16 v[86:87], v202 offset:2624
	ds_read_b64_tr_b16 v[88:89], v202 offset:3904
	s_waitcnt lgkmcnt(0)
	s_waitcnt vmcnt(7)
	ds_write_b128 v201, v[32:35]
	s_waitcnt vmcnt(6)
	ds_write_b128 v201, v[36:39] offset:1280
	s_waitcnt vmcnt(5)
	ds_write_b128 v201, v[40:43] offset:2560
	s_waitcnt vmcnt(4)
	ds_write_b128 v201, v[44:47] offset:3840
	v_cvt_pk_bf16_f32 v32, v61, v62
	v_cvt_pk_bf16_f32 v33, v63, v64
	v_cvt_pk_bf16_f32 v34, v65, v66
	v_cvt_pk_bf16_f32 v35, v67, v68
	v_cvt_pk_bf16_f32 v36, v69, v70
	v_cvt_pk_bf16_f32 v37, v71, v72
	v_cvt_pk_bf16_f32 v38, v73, v74
	v_cvt_pk_bf16_f32 v39, v75, v76
	s_waitcnt lgkmcnt(0)
; #define LAS __attribute__((address_space(3)))
; __device__ __forceinline__ void at32_load_qk(const Args& A, const At32& T, int lane, bf16x8 (&qf)[4], bf16x8 (&kf)[5][4]) {
;     const int L = SEQ >> T.dsh, q32 = lane & 31, h = lane >> 5, lk0 = T.lq0 - 64;
; __device__ __forceinline__ void at_task32(const Args& A, const At32& T, const At32& Tn, bf16x8 (&qf)[4], bf16x8 (&kf)[5][4], LAS unsigned char* lds, LAS unsigned char* vst, int lane) {
;     ...
;     for (int tile = 0; tile < 5; ++tile) {
; #pragma unroll
;         for (int it = 0; it < 4; ++it) { const int idx = it * 64 + lane, row = idx >> 3, ch = idx & 7; *(LAS u32x4*)(vst + row * VS_STRIDE + ch * 16) = vr[(tile & 1) * 4 + it]; }
;         if (tile < 3) {
; #pragma unroll
;             for (int it = 0; it < 4; ++it) { const int row = 32 * (tile + 2) + 8 * it + (lane >> 3); int lk = lk0 + row; lk = lk < 0 ? 0 : (lk > L - 1 ? L - 1 : lk);
;                 vr[(tile & 1) * 4 + it] = *(const u32x4*)(Vb + ((unsigned)((lk << dsh) + r) * 2048u + 16u * (lane & 7))); }
;         }
;         bf16x8 pf[2];
; #pragma unroll
;         for (int ks = 0; ks < 2; ++ks) { u32x4 pw; pw.x = cvt_pk_bf16(s[tile][8 * ks + 0], s[tile][8 * ks + 1]); pw.y = cvt_pk_bf16(s[tile][8 * ks + 2], s[tile][8 * ks + 3]);
;             pw.z = cvt_pk_bf16(s[tile][8 * ks + 4], s[tile][8 * ks + 5]); pw.w = cvt_pk_bf16(s[tile][8 * ks + 6], s[tile][8 * ks + 7]); pf[ks] = __builtin_bit_cast(bf16x8, pw); }
;         asm volatile("s_waitcnt lgkmcnt(0)" ::: "memory");
; #pragma unroll
;         for (int ks = 0; ks < 2; ++ks)
; #pragma unroll
;             for (int db = 0; db < 2; ++db) { const bf16x8 af = tr_pair(trb + (16 * ks) * VS_STRIDE + db * 64, trb + (16 * ks + 8) * VS_STRIDE + db * 64);
;                 o[db] = __builtin_amdgcn_mfma_f32_32x32x16_bf16(af, pf[ks], o[db], 0, 0, 0); }
;         asm volatile("s_waitcnt lgkmcnt(0)" ::: "memory");
;     }
;     asm volatile("" ::: "memory");
;     at32_load_qk(A, Tn, lane, qf, kf);
;     asm volatile("" ::: "memory");
;     const int ql = qoff + (q32 << dsh);
;     LAS unsigned char* orow = lds + ql * OB_STRIDE + 8 * h;
;     float ca = 0.f, cbb = 1.f, mn = mx, ln = lsum;
;     if (mode != 0) { const f32x2 ml = *(const LAS f32x2*)(ML + 2 * ql); mn = fmaxf(ml[0], mx); ca = __builtin_amdgcn_exp2f(ml[0] - mn); cbb = __builtin_amdgcn_exp2f(mx - mn); ln = ca * ml[1] + cbb * lsum; }
	ds_read_b64_tr_b16 v[40:41], v202
	ds_read_b64_tr_b16 v[42:43], v202 offset:1280
	s_waitcnt lgkmcnt(6)
	v_mfma_f32_32x32x16_bf16 v[0:15], v[86:89], v[82:85], v[0:15]
	s_waitcnt lgkmcnt(0)
	v_mfma_f32_32x32x16_bf16 v[16:31], v[40:43], v[32:35], v[16:31]
	ds_read_b64_tr_b16 v[40:41], v202 offset:64
	ds_read_b64_tr_b16 v[42:43], v202 offset:1344
	s_waitcnt lgkmcnt(0)
	v_mfma_f32_32x32x16_bf16 v[0:15], v[40:43], v[32:35], v[0:15]
	ds_read_b64_tr_b16 v[32:33], v202 offset:2560
	ds_read_b64_tr_b16 v[34:35], v202 offset:3840
	s_waitcnt lgkmcnt(0)
	v_mfma_f32_32x32x16_bf16 v[16:31], v[32:35], v[36:39], v[16:31]
	ds_read_b64_tr_b16 v[32:33], v202 offset:2624
	ds_read_b64_tr_b16 v[34:35], v202 offset:3904
	s_waitcnt lgkmcnt(0)
	s_waitcnt vmcnt(3)
	ds_write_b128 v201, v[48:51]
	s_waitcnt vmcnt(2)
	ds_write_b128 v201, v[52:55] offset:1280
	s_waitcnt vmcnt(1)
	ds_write_b128 v201, v[94:97] offset:2560
	s_waitcnt vmcnt(0)
	ds_write_b128 v201, v[98:101] offset:3840
	s_waitcnt lgkmcnt(4)
	v_mfma_f32_32x32x16_bf16 v[0:15], v[32:35], v[36:39], v[0:15]
	v_cvt_pk_bf16_f32 v32, v56, v57
	v_cvt_pk_bf16_f32 v33, v58, v59
	v_cvt_pk_bf16_f32 v34, v60, v112
	v_cvt_pk_bf16_f32 v35, v113, v114
	v_cvt_pk_bf16_f32 v36, v115, v116
	v_cvt_pk_bf16_f32 v37, v117, v118
	v_cvt_pk_bf16_f32 v38, v119, v120
	v_cvt_pk_bf16_f32 v39, v121, v122
	s_waitcnt lgkmcnt(0)
	ds_read_b64_tr_b16 v[40:41], v202
	ds_read_b64_tr_b16 v[42:43], v202 offset:1280
	s_waitcnt lgkmcnt(0)
	v_mfma_f32_32x32x16_bf16 v[16:31], v[40:43], v[32:35], v[16:31]
	ds_read_b64_tr_b16 v[40:41], v202 offset:64
	ds_read_b64_tr_b16 v[42:43], v202 offset:1344
	v_add_u32_e32 v52, s17, v169
	v_cmp_lt_i32_e32 vcc, 63, v52
	v_subrev_u32_e32 v48, 32, v52
	s_waitcnt lgkmcnt(0)
	v_mfma_f32_32x32x16_bf16 v[0:15], v[40:43], v[32:35], v[0:15]
	ds_read_b64_tr_b16 v[32:33], v202 offset:2560
	ds_read_b64_tr_b16 v[34:35], v202 offset:3840
	s_waitcnt lgkmcnt(0)
	v_mfma_f32_32x32x16_bf16 v[16:31], v[32:35], v[36:39], v[16:31]
	ds_read_b64_tr_b16 v[32:33], v202 offset:2624
	ds_read_b64_tr_b16 v[34:35], v202 offset:3904
	s_waitcnt lgkmcnt(0)
	s_waitcnt lgkmcnt(0)
	v_mfma_f32_32x32x16_bf16 v[0:15], v[32:35], v[36:39], v[0:15]
	v_lshlrev_b32_e32 v32, s23, v52
	v_add_u32_e32 v32, s16, v32
	v_lshl_or_b32 v32, v32, 11, v170
	global_load_dwordx4 v[68:71], v32, s[34:35]
	global_load_dwordx4 v[72:75], v32, s[34:35] offset:32
	global_load_dwordx4 v[94:97], v32, s[34:35] offset:64
	global_load_dwordx4 v[64:67], v32, s[34:35] offset:96
	v_readlane_b32 s34, v253, 53
	v_readlane_b32 s35, v253, 54
	s_add_u32 s6, s34, s3
	s_addc_u32 s7, s35, s7
	v_subrev_u32_e32 v32, 64, v52
	s_add_i32 s22, s22, -1
	v_min_i32_e32 v32, s22, v32
	v_cndmask_b32_e32 v32, 0, v32, vcc
	v_min_i32_e32 v48, s22, v48
	v_cmp_lt_i32_e32 vcc, 31, v52
	v_lshlrev_b32_e32 v32, s23, v32
	v_add_u32_e32 v32, s16, v32
	v_cndmask_b32_e32 v48, 0, v48, vcc
	v_lshlrev_b32_e32 v48, s23, v48
	v_add_u32_e32 v48, s16, v48
	v_lshl_or_b32 v44, v32, 11, v170
	v_lshl_or_b32 v53, v48, 11, v170
	global_load_dwordx4 v[32:35], v44, s[6:7]
	global_load_dwordx4 v[36:39], v44, s[6:7] offset:32
	global_load_dwordx4 v[40:43], v44, s[6:7] offset:64
	s_nop 0
	global_load_dwordx4 v[44:47], v44, s[6:7] offset:96
	s_nop 0
	global_load_dwordx4 v[48:51], v53, s[6:7]
	global_load_dwordx4 v[98:101], v53, s[6:7] offset:32
	global_load_dwordx4 v[102:105], v53, s[6:7] offset:64
	global_load_dwordx4 v[106:109], v53, s[6:7] offset:96
	v_min_i32_e32 v53, s22, v52
	v_cmp_lt_i32_e32 vcc, -1, v52
	s_cmp_lg_u32 s11, 0
	s_cselect_b64 s[34:35], -1, 0
	v_cndmask_b32_e32 v53, 0, v53, vcc
	v_lshlrev_b32_e32 v53, s23, v53
	v_add_u32_e32 v53, s16, v53
	v_lshl_or_b32 v53, v53, 11, v170
	global_load_dwordx4 v[114:117], v53, s[6:7]
	global_load_dwordx4 v[118:121], v53, s[6:7] offset:32
	global_load_dwordx4 v[122:125], v53, s[6:7] offset:64
	global_load_dwordx4 v[110:113], v53, s[6:7] offset:96
	v_add_u32_e32 v53, 32, v52
	v_min_i32_e32 v53, s22, v53
	v_cmp_lt_i32_e32 vcc, s2, v52
	s_cmp_eq_u32 s11, 0
	s_nop 0
	v_cndmask_b32_e32 v53, 0, v53, vcc
	v_lshlrev_b32_e32 v53, s23, v53
	v_add_u32_e32 v53, s16, v53
	v_lshl_or_b32 v53, v53, 11, v170
	global_load_dwordx4 v[126:129], v53, s[6:7]
	global_load_dwordx4 v[130:133], v53, s[6:7] offset:32
	global_load_dwordx4 v[134:137], v53, s[6:7] offset:64
	global_load_dwordx4 v[138:141], v53, s[6:7] offset:96
	v_add_u32_e32 v53, 64, v52
	v_min_i32_e32 v53, s22, v53
	v_cmp_lt_i32_e32 vcc, s18, v52
	s_nop 1
	v_cndmask_b32_e32 v52, 0, v53, vcc
	v_lshlrev_b32_e32 v52, s23, v52
	v_add_u32_e32 v52, s16, v52
	v_lshl_or_b32 v52, v52, 11, v170
	global_load_dwordx4 v[146:149], v52, s[6:7]
	global_load_dwordx4 v[150:153], v52, s[6:7] offset:32
	global_load_dwordx4 v[154:157], v52, s[6:7] offset:64
	global_load_dwordx4 v[142:145], v52, s[6:7] offset:96
	v_lshlrev_b32_e32 v52, s27, v169
	v_add_u32_e32 v54, s33, v52
	v_lshl_add_u32 v62, v54, 3, 0
	s_cbranch_scc1 .LBB0_388
	v_add_u32_e32 v52, 0x12000, v62
	ds_read_b64 v[52:53], v52
	v_max_f32_e32 v55, v80, v80
	s_waitcnt lgkmcnt(0)
	v_max_f32_e32 v56, v52, v52
	v_max_f32_e32 v55, v56, v55
	v_sub_f32_e32 v52, v52, v55
	v_sub_f32_e32 v57, v80, v55
	v_exp_f32_e32 v56, v52
	v_exp_f32_e32 v57, v57
	v_mov_b32_e32 v80, v53
	v_mov_b32_e32 v53, v56
	v_pk_mul_f32 v[58:59], v[80:81], v[56:57]
	v_mov_b32_e32 v52, v57
	v_add_f32_e32 v81, v58, v59
	v_mov_b32_e32 v80, v55
	s_cmp_lg_u32 s11, 2
	s_cbranch_scc1 .LBB0_411
